# QKV epilogue: qk-norm gain loads issued together (one wait); O-proj layer-0 epilogue: warm L2 with the f32 residual lines before the per-row loop
# speedup vs baseline: 1.0109x; 1.0109x over previous
; #define SSQ WSL(float, WS_SSQ)
;     __device__ __forceinline__ void operator()(const f32x4 (&acc)[2][2][4][2], const Unit& u, int wr, int wc, int fr_in, int fq_in) const {
;     ...
;                 for (int i = 0; i < 4; ++i) g[bj][n][i] = donorm ? gain[32 * bj + 8 * fq + 4 * n + i] * sc : sc;
;         f32x4 sq[2][4];
; #pragma unroll
;         for (int ai = 0; ai < 2; ++ai)
; #pragma unroll
;             for (int m = 0; m < 4; ++m) sq[ai][m] = *(const f32x4*)(SSQ + (size_t)(u.pm * BM + ai * HALF + wr * 64 + m * 16 + fr) * 4);
; #pragma unroll
;         for (int ai = 0; ai < 2; ++ai) {
; #pragma unroll
;           for (int mp = 0; mp < 4; ++mp) {
;             f32x4 rp4[4][4];
;             if (dorope) {
; #pragma unroll
;                 for (int m = mp; m < mp + 1; ++m) { const f32x4* rp = (const f32x4*)(rope + (size_t)((u.pm * BM + ai * HALF + wr * 64 + m * 16 + fr) & 4095) * 32 + 8 * fq);
; #pragma unroll
;                     for (int k = 0; k < 4; ++k) rp4[m][k] = rp[k]; }
.LBB0_221:
	s_andn2_b64 vcc, exec, s[2:3]
	s_cbranch_vccnz .LBB0_236
	v_lshlrev_b32_e32 v228, 3, v0
	v_ashrrev_i32_e32 v229, 31, v228
	v_mov_b32_e32 v190, s43
	v_mov_b32_e32 v191, s43
	v_mov_b32_e32 v242, s43
	v_mov_b32_e32 v193, s43
	v_mov_b32_e32 v194, s43
	v_mov_b32_e32 v195, s43
	v_mov_b32_e32 v243, s43
	v_mov_b32_e32 v197, s43
	v_mov_b32_e32 v198, s43
	v_mov_b32_e32 v199, s43
	v_mov_b32_e32 v244, s43
	v_mov_b32_e32 v192, s43
	v_mov_b32_e32 v212, s43
	v_mov_b32_e32 v213, s43
	v_mov_b32_e32 v245, s43
	v_mov_b32_e32 v196, s43
	s_xor_b64 s[2:3], s[4:5], -1
	s_and_b64 vcc, exec, s[4:5]
	s_cbranch_vccz .Lqkv_gains_done
	v_lshl_add_u64 v[114:115], v[228:229], 2, s[58:59]
	global_load_dword v190, v[114:115], off
	global_load_dword v191, v[114:115], off offset:4
	global_load_dword v242, v[114:115], off offset:8
	global_load_dword v193, v[114:115], off offset:12
	global_load_dword v194, v[114:115], off offset:16
	global_load_dword v195, v[114:115], off offset:20
	global_load_dword v243, v[114:115], off offset:24
	global_load_dword v197, v[114:115], off offset:28
	global_load_dword v198, v[114:115], off offset:128
	global_load_dword v199, v[114:115], off offset:132
	global_load_dword v244, v[114:115], off offset:136
	global_load_dword v192, v[114:115], off offset:140
	global_load_dword v212, v[114:115], off offset:144
	global_load_dword v213, v[114:115], off offset:148
	global_load_dword v245, v[114:115], off offset:152
	global_load_dword v196, v[114:115], off offset:156
	s_waitcnt vmcnt(0)
	v_mul_f32_e32 v190, s43, v190
	v_mul_f32_e32 v191, s43, v191
	v_mul_f32_e32 v242, s43, v242
	v_mul_f32_e32 v193, s43, v193
	v_mul_f32_e32 v194, s43, v194
	v_mul_f32_e32 v195, s43, v195
	v_mul_f32_e32 v243, s43, v243
	v_mul_f32_e32 v197, s43, v197
	v_mul_f32_e32 v198, s43, v198
	v_mul_f32_e32 v199, s43, v199
	v_mul_f32_e32 v244, s43, v244
	v_mul_f32_e32 v192, s43, v192
	v_mul_f32_e32 v212, s43, v212
	v_mul_f32_e32 v213, s43, v213
	v_mul_f32_e32 v245, s43, v245
	v_mul_f32_e32 v196, s43, v196
.Lqkv_gains_done:
	s_mov_b64 s[60:61], -1
	s_branch .LBB0_257
.LBB0_236:
	s_andn2_b64 vcc, exec, s[0:1]
	s_mov_b64 s[0:1], -1
	s_cbranch_vccnz .LBB0_199
	s_branch .LBB0_322
.LBB0_257:
	s_lshl_b32 s2, s48, 8
	s_add_i32 s2, s2, s70
	v_add_u32_e32 v230, s2, v241
	v_add_u32_e32 v226, 16, v230
	v_ashrrev_i32_e32 v231, 31, v230
	v_ashrrev_i32_e32 v227, 31, v226
	v_add_u32_e32 v224, 32, v230
	v_add_u32_e32 v222, 48, v230
	v_lshl_add_u64 v[114:115], v[230:231], 4, s[36:37]
	v_lshl_add_u64 v[116:117], v[226:227], 4, s[36:37]
	v_ashrrev_i32_e32 v225, 31, v224
	v_ashrrev_i32_e32 v223, 31, v222
	v_add_u32_e32 v220, 0x80, v230
	v_add_u32_e32 v218, 0x90, v230
	global_load_dwordx4 v[174:177], v[114:115], off
	global_load_dwordx4 v[170:173], v[116:117], off
	v_lshl_add_u64 v[114:115], v[224:225], 4, s[36:37]
	v_lshl_add_u64 v[116:117], v[222:223], 4, s[36:37]
	v_ashrrev_i32_e32 v221, 31, v220
	v_ashrrev_i32_e32 v219, 31, v218
	v_add_u32_e32 v216, 0xa0, v230
	v_add_u32_e32 v200, 0xb0, v230
	global_load_dwordx4 v[166:169], v[114:115], off
	global_load_dwordx4 v[162:165], v[116:117], off
	v_lshl_add_u64 v[114:115], v[220:221], 4, s[36:37]
	v_lshl_add_u64 v[116:117], v[218:219], 4, s[36:37]
	v_ashrrev_i32_e32 v217, 31, v216
	v_ashrrev_i32_e32 v201, 31, v200
	global_load_dwordx4 v[158:161], v[114:115], off
	global_load_dwordx4 v[138:141], v[116:117], off
	v_lshl_add_u64 v[114:115], v[216:217], 4, s[36:37]
	v_lshl_add_u64 v[116:117], v[200:201], 4, s[36:37]
	global_load_dwordx4 v[126:129], v[114:115], off
	s_nop 0
	global_load_dwordx4 v[114:117], v[116:117], off
	v_cndmask_b32_e64 v0, 0, 1, s[52:53]
	v_cmp_ne_u32_e64 s[2:3], 1, v0
	s_andn2_b64 vcc, exec, s[52:53]
	v_lshl_add_u64 v[214:215], v[228:229], 3, s[34:35]
	s_cbranch_vccnz .LBB0_259
	s_lshl_b32 s41, s48, 13
	s_add_i32 s41, s41, s73
	v_lshl_add_u32 v0, v241, 5, s41
	v_and_b32_e32 v0, 0x1ffe0, v0
	v_lshlrev_b32_e32 v0, 3, v0
	v_lshl_add_u64 v[150:151], v[214:215], 0, v[0:1]
	global_load_dwordx4 v[146:149], v[150:151], off offset:48
	global_load_dwordx4 v[142:145], v[150:151], off offset:32
	global_load_dwordx4 v[154:157], v[150:151], off offset:16
	s_nop 0
	global_load_dwordx4 v[150:153], v[150:151], off

;     __device__ __forceinline__ void operator()(const f32x4 (&acc)[2][2][4][2], const Unit& u, int wr, int wc, int fr_in, int fq_in) const {
;     ...
;             for (int m = 0; m < 4; ++m) { const int rl = ai * HALF + wr * 64 + m * 16 + fr; const size_t off = (size_t)(u.pm * BM + rl) * ldc + col0;
;                 float ss = 0.f;
; #pragma unroll
;                 for (int bj = 0; bj < 2; ++bj) {
;                     f32x4 b0, b1;
;                     if (base32) { b0 = *(const f32x4*)(base32 + off + bj * HALF); b1 = *(const f32x4*)(base32 + off + bj * HALF + 4); }
.LBB0_877:
	s_lshl_b32 s2, s20, 8
	v_mov_b32_e32 v232, v229
	v_mov_b32_e32 v233, v228
	s_or_b32 s2, s2, s44
	v_cndmask_b32_e64 v66, 0, 1, s[18:19]
	v_lshl_add_u32 v222, v233, 3, s2
	s_lshl_b32 s21, s21, 8
	v_cmp_ne_u32_e64 s[2:3], 1, v66
	s_andn2_b64 vcc, exec, s[18:19]
	v_ashrrev_i32_e32 v223, 31, v222
	v_add_u32_e32 v196, s43, v232
	s_cbranch_vccnz .LBB0_898
	v_add_u32_e32 v234, s43, v232
	v_add_u32_e32 v194, s21, v234
	v_ashrrev_i32_e32 v195, 31, v194
	v_lshlrev_b64 v[66:67], 10, v[194:195]
	v_lshl_add_u64 v[66:67], v[222:223], 0, v[66:67]
	v_lshl_add_u64 v[66:67], v[66:67], 2, s[8:9]
	s_mov_b32 s98, 0x10000
	s_mov_b32 s99, 0
	global_load_dword v70, v[66:67], off
	global_load_dword v70, v[66:67], off offset:512
	v_lshl_add_u64 v[66:67], v[66:67], 0, s[98:99]
	global_load_dword v70, v[66:67], off
	global_load_dword v70, v[66:67], off offset:512
	v_lshl_add_u64 v[66:67], v[66:67], 0, s[98:99]
	global_load_dword v70, v[66:67], off
	global_load_dword v70, v[66:67], off offset:512
	v_lshl_add_u64 v[66:67], v[66:67], 0, s[98:99]
	global_load_dword v70, v[66:67], off
	global_load_dword v70, v[66:67], off offset:512
	s_mov_b32 s98, 0x50000
	v_lshl_add_u64 v[66:67], v[66:67], 0, s[98:99]
	s_mov_b32 s98, 0x10000
	global_load_dword v70, v[66:67], off
	global_load_dword v70, v[66:67], off offset:512
	v_lshl_add_u64 v[66:67], v[66:67], 0, s[98:99]
	global_load_dword v70, v[66:67], off
	global_load_dword v70, v[66:67], off offset:512
	v_lshl_add_u64 v[66:67], v[66:67], 0, s[98:99]
	global_load_dword v70, v[66:67], off
	global_load_dword v70, v[66:67], off offset:512
	v_lshl_add_u64 v[66:67], v[66:67], 0, s[98:99]
	global_load_dword v70, v[66:67], off
	global_load_dword v70, v[66:67], off offset:512
	s_mov_b64 s[4:5], 0
	s_andn2_b64 vcc, exec, s[4:5]
	s_cbranch_vccnz .LBB0_880
